# GEMM K-loops: DMA issue split in two bursts of 4 spread over both K-step halves (B tile one half-step later), 1 DMA per 4 MFMAs
# speedup vs baseline: 1.0219x; 1.0192x over previous
.LBB0_241:
	s_mov_b64 s[8:9], 0x80
	v_lshl_add_u64 v[114:115], v[114:115], 0, s[8:9]
	v_mov_b32_e32 v38, 0
	s_mov_b32 s3, s2
	v_lshl_add_u64 v[116:117], v[114:115], 0, v[100:101]
	v_lshl_add_u64 v[118:119], v[114:115], 0, v[102:103]
	v_lshl_add_u64 v[120:121], v[114:115], 0, v[104:105]
	s_mov_b64 s[4:5], 0
	s_mov_b32 s2, 0
	v_readfirstlane_b32 s60, v98
	v_readfirstlane_b32 s61, v99
	v_readfirstlane_b32 s62, v114
	v_readfirstlane_b32 s63, v115
	v_readfirstlane_b32 s64, v122
	v_subrev_u32_e32 v140, s60, v98
	v_subrev_u32_e32 v144, s62, v114
	v_subrev_u32_e32 v145, s62, v116
	v_subrev_u32_e32 v146, s62, v118
	v_subrev_u32_e32 v147, s62, v120
	v_add_u32_e32 v141, 0x10000, v140
	v_add_u32_e32 v142, 0x20000, v140
	v_add_u32_e32 v143, 0x30000, v140
	v_add3_u32 v136, v131, v132, v133
	v_add3_u32 v137, v131, v134, v133
	v_add3_u32 v138, v130, v132, v133
	v_add3_u32 v139, v130, v134, v133
	s_add_u32 s60, s60, 0x80
	s_addc_u32 s61, s61, 0
	s_add_u32 m0, s64, 0x8000
	v_mov_b32_e32 v39, v38
	global_load_lds_dwordx4 v140, s[60:61]
	v_mov_b32_e32 v40, v38
	v_mov_b32_e32 v41, v38
	v_mov_b32_e32 v2, v38
	s_add_u32 m0, s64, 0x9000
	v_mov_b32_e32 v3, v38
	global_load_lds_dwordx4 v141, s[60:61]
	v_mov_b32_e32 v4, v38
	v_mov_b32_e32 v5, v38
	v_mov_b32_e32 v6, v38
	s_add_u32 m0, s64, 0xa000
	v_mov_b32_e32 v7, v38
	global_load_lds_dwordx4 v142, s[60:61]
	v_mov_b32_e32 v8, v38
	v_mov_b32_e32 v9, v38
	v_mov_b32_e32 v10, v38
	s_add_u32 m0, s64, 0xb000
	v_mov_b32_e32 v11, v38
	global_load_lds_dwordx4 v143, s[60:61]
	v_mov_b32_e32 v12, v38
	v_mov_b32_e32 v13, v38
	v_mov_b32_e32 v14, v38
	v_mov_b32_e32 v15, v38
	v_mov_b32_e32 v16, v38
	v_mov_b32_e32 v17, v38
	v_mov_b32_e32 v18, v38
	v_mov_b32_e32 v19, v38
	v_mov_b32_e32 v20, v38
	v_mov_b32_e32 v21, v38
	v_mov_b32_e32 v22, v38
	v_mov_b32_e32 v23, v38
	v_mov_b32_e32 v24, v38
	v_mov_b32_e32 v25, v38
	v_mov_b32_e32 v26, v38
	v_mov_b32_e32 v27, v38
	v_mov_b32_e32 v28, v38
	v_mov_b32_e32 v29, v38
	v_mov_b32_e32 v30, v38
	v_mov_b32_e32 v31, v38
	v_mov_b32_e32 v32, v38
	v_mov_b32_e32 v33, v38
	v_mov_b32_e32 v34, v38
	v_mov_b32_e32 v35, v38
	v_mov_b32_e32 v36, v38
	v_mov_b32_e32 v37, v38
	v_mov_b32_e32 v42, v38
	v_mov_b32_e32 v43, v38
	v_mov_b32_e32 v44, v38
	v_mov_b32_e32 v45, v38
	v_mov_b32_e32 v46, v38
	v_mov_b32_e32 v47, v38
	v_mov_b32_e32 v48, v38
	v_mov_b32_e32 v49, v38
	v_mov_b32_e32 v50, v38
	v_mov_b32_e32 v51, v38
	v_mov_b32_e32 v52, v38
	v_mov_b32_e32 v53, v38
	v_mov_b32_e32 v54, v38
	v_mov_b32_e32 v55, v38
	v_mov_b32_e32 v56, v38
	v_mov_b32_e32 v57, v38
	v_mov_b32_e32 v58, v38
	v_mov_b32_e32 v59, v38
	v_mov_b32_e32 v60, v38
	v_mov_b32_e32 v61, v38
	v_mov_b32_e32 v62, v38
	v_mov_b32_e32 v63, v38
	v_mov_b32_e32 v64, v38
	v_mov_b32_e32 v65, v38
	s_add_u32 s60, s60, 0x80
	s_addc_u32 s61, s61, 0
	s_mov_b64 s[10:11], 0x10080
	s_mov_b64 s[12:13], 0x20080
	s_mov_b64 s[14:15], 0x30080
	s_waitcnt vmcnt(4) lgkmcnt(0)
	s_barrier
	ds_read_b128 v[66:69], v136 offset:0
	ds_read_b128 v[82:85], v137 offset:16384
	ds_read_b128 v[86:89], v137 offset:18432
	ds_read_b128 v[70:73], v136 offset:2048
	ds_read_b128 v[90:93], v137 offset:20480
	ds_read_b128 v[94:97], v137 offset:22528
	ds_read_b128 v[74:77], v136 offset:4096
	ds_read_b128 v[78:81], v136 offset:6144
	s_mov_b32 s65, 7
.Lodwin_loop:
	ds_read_b128 v[148:151], v138 offset:0
	ds_read_b128 v[172:175], v139 offset:16384
	ds_read_b128 v[176:179], v139 offset:18432
	ds_read_b128 v[152:155], v138 offset:2048
	ds_read_b128 v[180:183], v139 offset:20480
	ds_read_b128 v[184:187], v139 offset:22528
	ds_read_b128 v[156:159], v138 offset:4096
	ds_read_b128 v[168:171], v138 offset:6144
	s_waitcnt lgkmcnt(8)
	s_add_u32 m0, s64, 0xc000
	v_mfma_f32_16x16x32_bf16 v[62:65], v[66:69], v[82:85], v[62:65]
	v_mfma_f32_16x16x32_bf16 v[58:61], v[66:69], v[86:89], v[58:61]
	global_load_lds_dwordx4 v144, s[62:63]
	v_mfma_f32_16x16x32_bf16 v[54:57], v[66:69], v[90:93], v[54:57]
	v_mfma_f32_16x16x32_bf16 v[50:53], v[66:69], v[94:97], v[50:53]
	s_add_u32 m0, s64, 0xd000
	v_mfma_f32_16x16x32_bf16 v[46:49], v[70:73], v[82:85], v[46:49]
	v_mfma_f32_16x16x32_bf16 v[42:45], v[70:73], v[86:89], v[42:45]
	global_load_lds_dwordx4 v145, s[62:63]
	v_mfma_f32_16x16x32_bf16 v[34:37], v[70:73], v[90:93], v[34:37]
	v_mfma_f32_16x16x32_bf16 v[30:33], v[70:73], v[94:97], v[30:33]
	s_add_u32 m0, s64, 0xe000
	v_mfma_f32_16x16x32_bf16 v[26:29], v[74:77], v[82:85], v[26:29]
	v_mfma_f32_16x16x32_bf16 v[22:25], v[74:77], v[86:89], v[22:25]
	global_load_lds_dwordx4 v146, s[62:63]
	v_mfma_f32_16x16x32_bf16 v[18:21], v[74:77], v[90:93], v[18:21]
	v_mfma_f32_16x16x32_bf16 v[14:17], v[74:77], v[94:97], v[14:17]
	s_add_u32 m0, s64, 0xf000
	v_mfma_f32_16x16x32_bf16 v[10:13], v[78:81], v[82:85], v[10:13]
	v_mfma_f32_16x16x32_bf16 v[6:9], v[78:81], v[86:89], v[6:9]
	global_load_lds_dwordx4 v147, s[62:63]
	v_mfma_f32_16x16x32_bf16 v[2:5], v[78:81], v[90:93], v[2:5]
	v_mfma_f32_16x16x32_bf16 v[38:41], v[78:81], v[94:97], v[38:41]
	s_add_u32 s62, s62, 0x80
	s_addc_u32 s63, s63, 0
	s_waitcnt lgkmcnt(0)
	s_barrier
	s_add_u32 m0, s64, 0x0
	v_mfma_f32_16x16x32_bf16 v[62:65], v[148:151], v[172:175], v[62:65]
	global_load_lds_dwordx4 v140, s[60:61]
	v_mfma_f32_16x16x32_bf16 v[58:61], v[148:151], v[176:179], v[58:61]
	s_add_u32 m0, s64, 0x1000
	v_mfma_f32_16x16x32_bf16 v[54:57], v[148:151], v[180:183], v[54:57]
	global_load_lds_dwordx4 v141, s[60:61]
	v_mfma_f32_16x16x32_bf16 v[50:53], v[148:151], v[184:187], v[50:53]
	s_add_u32 m0, s64, 0x2000
	v_mfma_f32_16x16x32_bf16 v[46:49], v[152:155], v[172:175], v[46:49]
	global_load_lds_dwordx4 v142, s[60:61]
	v_mfma_f32_16x16x32_bf16 v[42:45], v[152:155], v[176:179], v[42:45]
	s_add_u32 m0, s64, 0x3000
	v_mfma_f32_16x16x32_bf16 v[34:37], v[152:155], v[180:183], v[34:37]
	global_load_lds_dwordx4 v143, s[60:61]
	v_mfma_f32_16x16x32_bf16 v[30:33], v[152:155], v[184:187], v[30:33]
	s_add_u32 s60, s60, 0x80
	s_addc_u32 s61, s61, 0
	s_waitcnt vmcnt(4)
	s_barrier
	ds_read_b128 v[66:69], v136 offset:32768
	ds_read_b128 v[82:85], v137 offset:49152
	ds_read_b128 v[86:89], v137 offset:51200
	ds_read_b128 v[70:73], v136 offset:34816
	ds_read_b128 v[90:93], v137 offset:53248
	ds_read_b128 v[94:97], v137 offset:55296
	ds_read_b128 v[74:77], v136 offset:36864
	ds_read_b128 v[78:81], v136 offset:38912
	v_mfma_f32_16x16x32_bf16 v[26:29], v[156:159], v[172:175], v[26:29]
	v_mfma_f32_16x16x32_bf16 v[22:25], v[156:159], v[176:179], v[22:25]
	v_mfma_f32_16x16x32_bf16 v[18:21], v[156:159], v[180:183], v[18:21]
	v_mfma_f32_16x16x32_bf16 v[14:17], v[156:159], v[184:187], v[14:17]
	v_mfma_f32_16x16x32_bf16 v[10:13], v[168:171], v[172:175], v[10:13]
	v_mfma_f32_16x16x32_bf16 v[6:9], v[168:171], v[176:179], v[6:9]
	v_mfma_f32_16x16x32_bf16 v[2:5], v[168:171], v[180:183], v[2:5]
	v_mfma_f32_16x16x32_bf16 v[38:41], v[168:171], v[184:187], v[38:41]
	ds_read_b128 v[148:151], v138 offset:32768
	ds_read_b128 v[172:175], v139 offset:49152
	ds_read_b128 v[176:179], v139 offset:51200
	ds_read_b128 v[152:155], v138 offset:34816
	ds_read_b128 v[180:183], v139 offset:53248
	ds_read_b128 v[184:187], v139 offset:55296
	ds_read_b128 v[156:159], v138 offset:36864
	ds_read_b128 v[168:171], v138 offset:38912
	s_waitcnt lgkmcnt(8)
	s_add_u32 m0, s64, 0x4000
	v_mfma_f32_16x16x32_bf16 v[62:65], v[66:69], v[82:85], v[62:65]
	v_mfma_f32_16x16x32_bf16 v[58:61], v[66:69], v[86:89], v[58:61]
	global_load_lds_dwordx4 v144, s[62:63]
	v_mfma_f32_16x16x32_bf16 v[54:57], v[66:69], v[90:93], v[54:57]
	v_mfma_f32_16x16x32_bf16 v[50:53], v[66:69], v[94:97], v[50:53]
	s_add_u32 m0, s64, 0x5000
	v_mfma_f32_16x16x32_bf16 v[46:49], v[70:73], v[82:85], v[46:49]
	v_mfma_f32_16x16x32_bf16 v[42:45], v[70:73], v[86:89], v[42:45]
	global_load_lds_dwordx4 v145, s[62:63]
	v_mfma_f32_16x16x32_bf16 v[34:37], v[70:73], v[90:93], v[34:37]
	v_mfma_f32_16x16x32_bf16 v[30:33], v[70:73], v[94:97], v[30:33]
	s_add_u32 m0, s64, 0x6000
	v_mfma_f32_16x16x32_bf16 v[26:29], v[74:77], v[82:85], v[26:29]
	v_mfma_f32_16x16x32_bf16 v[22:25], v[74:77], v[86:89], v[22:25]
	global_load_lds_dwordx4 v146, s[62:63]
	v_mfma_f32_16x16x32_bf16 v[18:21], v[74:77], v[90:93], v[18:21]
	v_mfma_f32_16x16x32_bf16 v[14:17], v[74:77], v[94:97], v[14:17]
	s_add_u32 m0, s64, 0x7000
	v_mfma_f32_16x16x32_bf16 v[10:13], v[78:81], v[82:85], v[10:13]
	v_mfma_f32_16x16x32_bf16 v[6:9], v[78:81], v[86:89], v[6:9]
	global_load_lds_dwordx4 v147, s[62:63]
	v_mfma_f32_16x16x32_bf16 v[2:5], v[78:81], v[90:93], v[2:5]
	v_mfma_f32_16x16x32_bf16 v[38:41], v[78:81], v[94:97], v[38:41]
	s_add_u32 s62, s62, 0x80
	s_addc_u32 s63, s63, 0
	s_waitcnt lgkmcnt(0)
	s_barrier
	s_add_u32 m0, s64, 0x8000
	v_mfma_f32_16x16x32_bf16 v[62:65], v[148:151], v[172:175], v[62:65]
	global_load_lds_dwordx4 v140, s[60:61]
	v_mfma_f32_16x16x32_bf16 v[58:61], v[148:151], v[176:179], v[58:61]
	s_add_u32 m0, s64, 0x9000
	v_mfma_f32_16x16x32_bf16 v[54:57], v[148:151], v[180:183], v[54:57]
	global_load_lds_dwordx4 v141, s[60:61]
	v_mfma_f32_16x16x32_bf16 v[50:53], v[148:151], v[184:187], v[50:53]
	s_add_u32 m0, s64, 0xa000
	v_mfma_f32_16x16x32_bf16 v[46:49], v[152:155], v[172:175], v[46:49]
	global_load_lds_dwordx4 v142, s[60:61]
	v_mfma_f32_16x16x32_bf16 v[42:45], v[152:155], v[176:179], v[42:45]
	s_add_u32 m0, s64, 0xb000
	v_mfma_f32_16x16x32_bf16 v[34:37], v[152:155], v[180:183], v[34:37]
	global_load_lds_dwordx4 v143, s[60:61]
	v_mfma_f32_16x16x32_bf16 v[30:33], v[152:155], v[184:187], v[30:33]
	s_add_u32 s60, s60, 0x80
	s_addc_u32 s61, s61, 0
	s_waitcnt vmcnt(4)
	s_barrier
	ds_read_b128 v[66:69], v136 offset:0
	ds_read_b128 v[82:85], v137 offset:16384
	ds_read_b128 v[86:89], v137 offset:18432
	ds_read_b128 v[70:73], v136 offset:2048
	ds_read_b128 v[90:93], v137 offset:20480
	ds_read_b128 v[94:97], v137 offset:22528
	ds_read_b128 v[74:77], v136 offset:4096
	ds_read_b128 v[78:81], v136 offset:6144
	v_mfma_f32_16x16x32_bf16 v[26:29], v[156:159], v[172:175], v[26:29]
	v_mfma_f32_16x16x32_bf16 v[22:25], v[156:159], v[176:179], v[22:25]
	v_mfma_f32_16x16x32_bf16 v[18:21], v[156:159], v[180:183], v[18:21]
	v_mfma_f32_16x16x32_bf16 v[14:17], v[156:159], v[184:187], v[14:17]
	v_mfma_f32_16x16x32_bf16 v[10:13], v[168:171], v[172:175], v[10:13]
	v_mfma_f32_16x16x32_bf16 v[6:9], v[168:171], v[176:179], v[6:9]
	v_mfma_f32_16x16x32_bf16 v[2:5], v[168:171], v[180:183], v[2:5]
	v_mfma_f32_16x16x32_bf16 v[38:41], v[168:171], v[184:187], v[38:41]
	s_sub_i32 s65, s65, 1
	s_cmp_lg_u32 s65, 0
	s_cbranch_scc1 .Lodwin_loop
	ds_read_b128 v[148:151], v138 offset:0
	ds_read_b128 v[172:175], v139 offset:16384
	ds_read_b128 v[176:179], v139 offset:18432
	ds_read_b128 v[152:155], v138 offset:2048
	ds_read_b128 v[180:183], v139 offset:20480
	ds_read_b128 v[184:187], v139 offset:22528
	ds_read_b128 v[156:159], v138 offset:4096
	ds_read_b128 v[168:171], v138 offset:6144
	s_waitcnt lgkmcnt(8)
	s_add_u32 m0, s64, 0xc000
	v_mfma_f32_16x16x32_bf16 v[62:65], v[66:69], v[82:85], v[62:65]
	v_mfma_f32_16x16x32_bf16 v[58:61], v[66:69], v[86:89], v[58:61]
	global_load_lds_dwordx4 v144, s[62:63]
	v_mfma_f32_16x16x32_bf16 v[54:57], v[66:69], v[90:93], v[54:57]
	v_mfma_f32_16x16x32_bf16 v[50:53], v[66:69], v[94:97], v[50:53]
	s_add_u32 m0, s64, 0xd000
	v_mfma_f32_16x16x32_bf16 v[46:49], v[70:73], v[82:85], v[46:49]
	v_mfma_f32_16x16x32_bf16 v[42:45], v[70:73], v[86:89], v[42:45]
	global_load_lds_dwordx4 v145, s[62:63]
	v_mfma_f32_16x16x32_bf16 v[34:37], v[70:73], v[90:93], v[34:37]
	v_mfma_f32_16x16x32_bf16 v[30:33], v[70:73], v[94:97], v[30:33]
	s_add_u32 m0, s64, 0xe000
	v_mfma_f32_16x16x32_bf16 v[26:29], v[74:77], v[82:85], v[26:29]
	v_mfma_f32_16x16x32_bf16 v[22:25], v[74:77], v[86:89], v[22:25]
	global_load_lds_dwordx4 v146, s[62:63]
	v_mfma_f32_16x16x32_bf16 v[18:21], v[74:77], v[90:93], v[18:21]
	v_mfma_f32_16x16x32_bf16 v[14:17], v[74:77], v[94:97], v[14:17]
	s_add_u32 m0, s64, 0xf000
	v_mfma_f32_16x16x32_bf16 v[10:13], v[78:81], v[82:85], v[10:13]
	v_mfma_f32_16x16x32_bf16 v[6:9], v[78:81], v[86:89], v[6:9]
	global_load_lds_dwordx4 v147, s[62:63]
	v_mfma_f32_16x16x32_bf16 v[2:5], v[78:81], v[90:93], v[2:5]
	v_mfma_f32_16x16x32_bf16 v[38:41], v[78:81], v[94:97], v[38:41]
	s_add_u32 s62, s62, 0x80
	s_addc_u32 s63, s63, 0
	s_waitcnt lgkmcnt(0)
	s_barrier
	v_mfma_f32_16x16x32_bf16 v[62:65], v[148:151], v[172:175], v[62:65]
	v_mfma_f32_16x16x32_bf16 v[58:61], v[148:151], v[176:179], v[58:61]
	v_mfma_f32_16x16x32_bf16 v[54:57], v[148:151], v[180:183], v[54:57]
	v_mfma_f32_16x16x32_bf16 v[50:53], v[148:151], v[184:187], v[50:53]
	v_mfma_f32_16x16x32_bf16 v[46:49], v[152:155], v[172:175], v[46:49]
	v_mfma_f32_16x16x32_bf16 v[42:45], v[152:155], v[176:179], v[42:45]
	v_mfma_f32_16x16x32_bf16 v[34:37], v[152:155], v[180:183], v[34:37]
	v_mfma_f32_16x16x32_bf16 v[30:33], v[152:155], v[184:187], v[30:33]
	s_waitcnt vmcnt(0)
	s_barrier
	ds_read_b128 v[66:69], v136 offset:32768
	ds_read_b128 v[82:85], v137 offset:49152
	ds_read_b128 v[86:89], v137 offset:51200
	ds_read_b128 v[70:73], v136 offset:34816
	ds_read_b128 v[90:93], v137 offset:53248
	ds_read_b128 v[94:97], v137 offset:55296
	ds_read_b128 v[74:77], v136 offset:36864
	ds_read_b128 v[78:81], v136 offset:38912
	v_mfma_f32_16x16x32_bf16 v[26:29], v[156:159], v[172:175], v[26:29]
	v_mfma_f32_16x16x32_bf16 v[22:25], v[156:159], v[176:179], v[22:25]
	v_mfma_f32_16x16x32_bf16 v[18:21], v[156:159], v[180:183], v[18:21]
	v_mfma_f32_16x16x32_bf16 v[14:17], v[156:159], v[184:187], v[14:17]
	v_mfma_f32_16x16x32_bf16 v[10:13], v[168:171], v[172:175], v[10:13]
	v_mfma_f32_16x16x32_bf16 v[6:9], v[168:171], v[176:179], v[6:9]
	v_mfma_f32_16x16x32_bf16 v[2:5], v[168:171], v[180:183], v[2:5]
	v_mfma_f32_16x16x32_bf16 v[38:41], v[168:171], v[184:187], v[38:41]
	ds_read_b128 v[148:151], v138 offset:32768
	ds_read_b128 v[172:175], v139 offset:49152
	ds_read_b128 v[176:179], v139 offset:51200
	ds_read_b128 v[152:155], v138 offset:34816
	ds_read_b128 v[180:183], v139 offset:53248
	ds_read_b128 v[184:187], v139 offset:55296
	ds_read_b128 v[156:159], v138 offset:36864
	ds_read_b128 v[168:171], v138 offset:38912
	s_waitcnt lgkmcnt(8)
	v_mfma_f32_16x16x32_bf16 v[62:65], v[66:69], v[82:85], v[62:65]
	v_mfma_f32_16x16x32_bf16 v[58:61], v[66:69], v[86:89], v[58:61]
	v_mfma_f32_16x16x32_bf16 v[54:57], v[66:69], v[90:93], v[54:57]
	v_mfma_f32_16x16x32_bf16 v[50:53], v[66:69], v[94:97], v[50:53]
	v_mfma_f32_16x16x32_bf16 v[46:49], v[70:73], v[82:85], v[46:49]
	v_mfma_f32_16x16x32_bf16 v[42:45], v[70:73], v[86:89], v[42:45]
	v_mfma_f32_16x16x32_bf16 v[34:37], v[70:73], v[90:93], v[34:37]
	v_mfma_f32_16x16x32_bf16 v[30:33], v[70:73], v[94:97], v[30:33]
	v_mfma_f32_16x16x32_bf16 v[26:29], v[74:77], v[82:85], v[26:29]
	v_mfma_f32_16x16x32_bf16 v[22:25], v[74:77], v[86:89], v[22:25]
	v_mfma_f32_16x16x32_bf16 v[18:21], v[74:77], v[90:93], v[18:21]
	v_mfma_f32_16x16x32_bf16 v[14:17], v[74:77], v[94:97], v[14:17]
	v_mfma_f32_16x16x32_bf16 v[10:13], v[78:81], v[82:85], v[10:13]
	v_mfma_f32_16x16x32_bf16 v[6:9], v[78:81], v[86:89], v[6:9]
	v_mfma_f32_16x16x32_bf16 v[2:5], v[78:81], v[90:93], v[2:5]
	v_mfma_f32_16x16x32_bf16 v[38:41], v[78:81], v[94:97], v[38:41]
	s_waitcnt lgkmcnt(0)
	s_barrier
	v_mfma_f32_16x16x32_bf16 v[62:65], v[148:151], v[172:175], v[62:65]
	v_mfma_f32_16x16x32_bf16 v[58:61], v[148:151], v[176:179], v[58:61]
	v_mfma_f32_16x16x32_bf16 v[54:57], v[148:151], v[180:183], v[54:57]
	v_mfma_f32_16x16x32_bf16 v[50:53], v[148:151], v[184:187], v[50:53]
	v_mfma_f32_16x16x32_bf16 v[46:49], v[152:155], v[172:175], v[46:49]
	v_mfma_f32_16x16x32_bf16 v[42:45], v[152:155], v[176:179], v[42:45]
	v_mfma_f32_16x16x32_bf16 v[34:37], v[152:155], v[180:183], v[34:37]
	v_mfma_f32_16x16x32_bf16 v[30:33], v[152:155], v[184:187], v[30:33]
	v_mfma_f32_16x16x32_bf16 v[26:29], v[156:159], v[172:175], v[26:29]
	v_mfma_f32_16x16x32_bf16 v[22:25], v[156:159], v[176:179], v[22:25]
	v_mfma_f32_16x16x32_bf16 v[18:21], v[156:159], v[180:183], v[18:21]
	v_mfma_f32_16x16x32_bf16 v[14:17], v[156:159], v[184:187], v[14:17]
	v_mfma_f32_16x16x32_bf16 v[10:13], v[168:171], v[172:175], v[10:13]
	v_mfma_f32_16x16x32_bf16 v[6:9], v[168:171], v[176:179], v[6:9]
	v_mfma_f32_16x16x32_bf16 v[2:5], v[168:171], v[180:183], v[2:5]
	v_mfma_f32_16x16x32_bf16 v[38:41], v[168:171], v[184:187], v[38:41]

.LBB0_508:
	v_cmp_gt_i32_e32 vcc, s2, v117
	s_mov_b64 s[0:1], 0x80
	v_lshl_add_u64 v[104:105], v[66:67], 0, s[0:1]
	v_cndmask_b32_e32 v0, 0, v199, vcc
	v_cmp_gt_i32_e32 vcc, s2, v119
	v_mov_b32_e32 v3, v1
	v_mov_b32_e32 v5, v1
	v_cndmask_b32_e32 v2, 0, v206, vcc
	v_cmp_gt_i32_e32 vcc, s2, v121
	v_mov_b32_e32 v42, 0
	s_mov_b32 s4, 0
	v_cndmask_b32_e32 v4, 0, v207, vcc
	v_lshl_add_u64 v[106:107], v[104:105], 0, v[0:1]
	v_lshl_add_u64 v[108:109], v[104:105], 0, v[2:3]
	v_lshl_add_u64 v[110:111], v[104:105], 0, v[4:5]
	s_mov_b64 s[0:1], 0
	v_readfirstlane_b32 s60, v98
	v_readfirstlane_b32 s61, v99
	v_readfirstlane_b32 s62, v104
	v_readfirstlane_b32 s63, v105
	v_readfirstlane_b32 s64, v112
	v_subrev_u32_e32 v140, s60, v98
	v_subrev_u32_e32 v144, s62, v104
	v_subrev_u32_e32 v145, s62, v106
	v_subrev_u32_e32 v146, s62, v108
	v_subrev_u32_e32 v147, s62, v110
	v_add_u32_e32 v141, 0x10000, v140
	v_add_u32_e32 v142, 0x20000, v140
	v_add_u32_e32 v143, 0x30000, v140
	v_add3_u32 v136, v124, v125, v126
	v_add3_u32 v137, v124, v127, v126
	v_add3_u32 v138, v123, v125, v126
	v_add3_u32 v139, v123, v127, v126
	s_add_u32 s60, s60, 0x80
	s_addc_u32 s61, s61, 0
	s_add_u32 m0, s64, 0x8000
	v_mov_b32_e32 v43, v42
	global_load_lds_dwordx4 v140, s[60:61]
	v_mov_b32_e32 v44, v42
	v_mov_b32_e32 v45, v42
	v_mov_b32_e32 v2, v42
	s_add_u32 m0, s64, 0x9000
	v_mov_b32_e32 v3, v42
	global_load_lds_dwordx4 v141, s[60:61]
	v_mov_b32_e32 v4, v42
	v_mov_b32_e32 v5, v42
	v_mov_b32_e32 v6, v42
	s_add_u32 m0, s64, 0xa000
	v_mov_b32_e32 v7, v42
	global_load_lds_dwordx4 v142, s[60:61]
	v_mov_b32_e32 v8, v42
	v_mov_b32_e32 v9, v42
	v_mov_b32_e32 v10, v42
	s_add_u32 m0, s64, 0xb000
	v_mov_b32_e32 v11, v42
	global_load_lds_dwordx4 v143, s[60:61]
	v_mov_b32_e32 v12, v42
	v_mov_b32_e32 v13, v42
	v_mov_b32_e32 v14, v42
	v_mov_b32_e32 v15, v42
	v_mov_b32_e32 v16, v42
	v_mov_b32_e32 v17, v42
	v_mov_b32_e32 v18, v42
	v_mov_b32_e32 v19, v42
	v_mov_b32_e32 v20, v42
	v_mov_b32_e32 v21, v42
	v_mov_b32_e32 v22, v42
	v_mov_b32_e32 v23, v42
	v_mov_b32_e32 v24, v42
	v_mov_b32_e32 v25, v42
	v_mov_b32_e32 v26, v42
	v_mov_b32_e32 v27, v42
	v_mov_b32_e32 v28, v42
	v_mov_b32_e32 v29, v42
	v_mov_b32_e32 v30, v42
	v_mov_b32_e32 v31, v42
	v_mov_b32_e32 v32, v42
	v_mov_b32_e32 v33, v42
	v_mov_b32_e32 v34, v42
	v_mov_b32_e32 v35, v42
	v_mov_b32_e32 v36, v42
	v_mov_b32_e32 v37, v42
	v_mov_b32_e32 v38, v42
	v_mov_b32_e32 v39, v42
	v_mov_b32_e32 v40, v42
	v_mov_b32_e32 v41, v42
	v_mov_b32_e32 v46, v42
	v_mov_b32_e32 v47, v42
	v_mov_b32_e32 v48, v42
	v_mov_b32_e32 v49, v42
	v_mov_b32_e32 v50, v42
	v_mov_b32_e32 v51, v42
	v_mov_b32_e32 v52, v42
	v_mov_b32_e32 v53, v42
	v_mov_b32_e32 v54, v42
	v_mov_b32_e32 v55, v42
	v_mov_b32_e32 v56, v42
	v_mov_b32_e32 v57, v42
	v_mov_b32_e32 v58, v42
	v_mov_b32_e32 v59, v42
	v_mov_b32_e32 v60, v42
	v_mov_b32_e32 v61, v42
	v_mov_b32_e32 v62, v42
	v_mov_b32_e32 v63, v42
	v_mov_b32_e32 v64, v42
	v_mov_b32_e32 v65, v42
	s_add_u32 s60, s60, 0x80
	s_addc_u32 s61, s61, 0
	s_mov_b64 s[12:13], 0x10000
	s_mov_b64 s[14:15], 0x20000
	s_mov_b64 s[16:17], 0x30000
	s_mov_b64 s[8:9], 0x10080
	s_mov_b64 s[10:11], 0x20080
	s_mov_b64 s[18:19], 0x30080
	s_waitcnt vmcnt(4) lgkmcnt(0)
	s_barrier
	ds_read_b128 v[66:69], v136 offset:0
	ds_read_b128 v[82:85], v137 offset:16384
	ds_read_b128 v[86:89], v137 offset:18432
	ds_read_b128 v[70:73], v136 offset:2048
	ds_read_b128 v[90:93], v137 offset:20480
	ds_read_b128 v[94:97], v137 offset:22528
	ds_read_b128 v[74:77], v136 offset:4096
	ds_read_b128 v[78:81], v136 offset:6144
	s_mov_b32 s65, 7
.Levwin_loop:
	ds_read_b128 v[148:151], v138 offset:0
	ds_read_b128 v[172:175], v139 offset:16384
	ds_read_b128 v[176:179], v139 offset:18432
	ds_read_b128 v[152:155], v138 offset:2048
	ds_read_b128 v[180:183], v139 offset:20480
	ds_read_b128 v[184:187], v139 offset:22528
	ds_read_b128 v[156:159], v138 offset:4096
	ds_read_b128 v[168:171], v138 offset:6144
	s_waitcnt lgkmcnt(8)
	s_add_u32 m0, s64, 0xc000
	v_mfma_f32_16x16x32_bf16 v[62:65], v[66:69], v[82:85], v[62:65]
	v_mfma_f32_16x16x32_bf16 v[58:61], v[66:69], v[86:89], v[58:61]
	global_load_lds_dwordx4 v144, s[62:63]
	v_mfma_f32_16x16x32_bf16 v[54:57], v[66:69], v[90:93], v[54:57]
	v_mfma_f32_16x16x32_bf16 v[50:53], v[66:69], v[94:97], v[50:53]
	s_add_u32 m0, s64, 0xd000
	v_mfma_f32_16x16x32_bf16 v[46:49], v[70:73], v[82:85], v[46:49]
	v_mfma_f32_16x16x32_bf16 v[38:41], v[70:73], v[86:89], v[38:41]
	global_load_lds_dwordx4 v145, s[62:63]
	v_mfma_f32_16x16x32_bf16 v[34:37], v[70:73], v[90:93], v[34:37]
	v_mfma_f32_16x16x32_bf16 v[30:33], v[70:73], v[94:97], v[30:33]
	s_add_u32 m0, s64, 0xe000
	v_mfma_f32_16x16x32_bf16 v[26:29], v[74:77], v[82:85], v[26:29]
	v_mfma_f32_16x16x32_bf16 v[22:25], v[74:77], v[86:89], v[22:25]
	global_load_lds_dwordx4 v146, s[62:63]
	v_mfma_f32_16x16x32_bf16 v[18:21], v[74:77], v[90:93], v[18:21]
	v_mfma_f32_16x16x32_bf16 v[14:17], v[74:77], v[94:97], v[14:17]
	s_add_u32 m0, s64, 0xf000
	v_mfma_f32_16x16x32_bf16 v[10:13], v[78:81], v[82:85], v[10:13]
	v_mfma_f32_16x16x32_bf16 v[6:9], v[78:81], v[86:89], v[6:9]
	global_load_lds_dwordx4 v147, s[62:63]
	v_mfma_f32_16x16x32_bf16 v[2:5], v[78:81], v[90:93], v[2:5]
	v_mfma_f32_16x16x32_bf16 v[42:45], v[78:81], v[94:97], v[42:45]
	s_add_u32 s62, s62, 0x80
	s_addc_u32 s63, s63, 0
	s_waitcnt lgkmcnt(0)
	s_barrier
	s_add_u32 m0, s64, 0x0
	v_mfma_f32_16x16x32_bf16 v[62:65], v[148:151], v[172:175], v[62:65]
	global_load_lds_dwordx4 v140, s[60:61]
	v_mfma_f32_16x16x32_bf16 v[58:61], v[148:151], v[176:179], v[58:61]
	s_add_u32 m0, s64, 0x1000
	v_mfma_f32_16x16x32_bf16 v[54:57], v[148:151], v[180:183], v[54:57]
	global_load_lds_dwordx4 v141, s[60:61]
	v_mfma_f32_16x16x32_bf16 v[50:53], v[148:151], v[184:187], v[50:53]
	s_add_u32 m0, s64, 0x2000
	v_mfma_f32_16x16x32_bf16 v[46:49], v[152:155], v[172:175], v[46:49]
	global_load_lds_dwordx4 v142, s[60:61]
	v_mfma_f32_16x16x32_bf16 v[38:41], v[152:155], v[176:179], v[38:41]
	s_add_u32 m0, s64, 0x3000
	v_mfma_f32_16x16x32_bf16 v[34:37], v[152:155], v[180:183], v[34:37]
	global_load_lds_dwordx4 v143, s[60:61]
	v_mfma_f32_16x16x32_bf16 v[30:33], v[152:155], v[184:187], v[30:33]
	s_add_u32 s60, s60, 0x80
	s_addc_u32 s61, s61, 0
	s_waitcnt vmcnt(4)
	s_barrier
	ds_read_b128 v[66:69], v136 offset:32768
	ds_read_b128 v[82:85], v137 offset:49152
	ds_read_b128 v[86:89], v137 offset:51200
	ds_read_b128 v[70:73], v136 offset:34816
	ds_read_b128 v[90:93], v137 offset:53248
	ds_read_b128 v[94:97], v137 offset:55296
	ds_read_b128 v[74:77], v136 offset:36864
	ds_read_b128 v[78:81], v136 offset:38912
	v_mfma_f32_16x16x32_bf16 v[26:29], v[156:159], v[172:175], v[26:29]
	v_mfma_f32_16x16x32_bf16 v[22:25], v[156:159], v[176:179], v[22:25]
	v_mfma_f32_16x16x32_bf16 v[18:21], v[156:159], v[180:183], v[18:21]
	v_mfma_f32_16x16x32_bf16 v[14:17], v[156:159], v[184:187], v[14:17]
	v_mfma_f32_16x16x32_bf16 v[10:13], v[168:171], v[172:175], v[10:13]
	v_mfma_f32_16x16x32_bf16 v[6:9], v[168:171], v[176:179], v[6:9]
	v_mfma_f32_16x16x32_bf16 v[2:5], v[168:171], v[180:183], v[2:5]
	v_mfma_f32_16x16x32_bf16 v[42:45], v[168:171], v[184:187], v[42:45]
	ds_read_b128 v[148:151], v138 offset:32768
	ds_read_b128 v[172:175], v139 offset:49152
	ds_read_b128 v[176:179], v139 offset:51200
	ds_read_b128 v[152:155], v138 offset:34816
	ds_read_b128 v[180:183], v139 offset:53248
	ds_read_b128 v[184:187], v139 offset:55296
	ds_read_b128 v[156:159], v138 offset:36864
	ds_read_b128 v[168:171], v138 offset:38912
	s_waitcnt lgkmcnt(8)
	s_add_u32 m0, s64, 0x4000
	v_mfma_f32_16x16x32_bf16 v[62:65], v[66:69], v[82:85], v[62:65]
	v_mfma_f32_16x16x32_bf16 v[58:61], v[66:69], v[86:89], v[58:61]
	global_load_lds_dwordx4 v144, s[62:63]
	v_mfma_f32_16x16x32_bf16 v[54:57], v[66:69], v[90:93], v[54:57]
	v_mfma_f32_16x16x32_bf16 v[50:53], v[66:69], v[94:97], v[50:53]
	s_add_u32 m0, s64, 0x5000
	v_mfma_f32_16x16x32_bf16 v[46:49], v[70:73], v[82:85], v[46:49]
	v_mfma_f32_16x16x32_bf16 v[38:41], v[70:73], v[86:89], v[38:41]
	global_load_lds_dwordx4 v145, s[62:63]
	v_mfma_f32_16x16x32_bf16 v[34:37], v[70:73], v[90:93], v[34:37]
	v_mfma_f32_16x16x32_bf16 v[30:33], v[70:73], v[94:97], v[30:33]
	s_add_u32 m0, s64, 0x6000
	v_mfma_f32_16x16x32_bf16 v[26:29], v[74:77], v[82:85], v[26:29]
	v_mfma_f32_16x16x32_bf16 v[22:25], v[74:77], v[86:89], v[22:25]
	global_load_lds_dwordx4 v146, s[62:63]
	v_mfma_f32_16x16x32_bf16 v[18:21], v[74:77], v[90:93], v[18:21]
	v_mfma_f32_16x16x32_bf16 v[14:17], v[74:77], v[94:97], v[14:17]
	s_add_u32 m0, s64, 0x7000
	v_mfma_f32_16x16x32_bf16 v[10:13], v[78:81], v[82:85], v[10:13]
	v_mfma_f32_16x16x32_bf16 v[6:9], v[78:81], v[86:89], v[6:9]
	global_load_lds_dwordx4 v147, s[62:63]
	v_mfma_f32_16x16x32_bf16 v[2:5], v[78:81], v[90:93], v[2:5]
	v_mfma_f32_16x16x32_bf16 v[42:45], v[78:81], v[94:97], v[42:45]
	s_add_u32 s62, s62, 0x80
	s_addc_u32 s63, s63, 0
	s_waitcnt lgkmcnt(0)
	s_barrier
	s_add_u32 m0, s64, 0x8000
	v_mfma_f32_16x16x32_bf16 v[62:65], v[148:151], v[172:175], v[62:65]
	global_load_lds_dwordx4 v140, s[60:61]
	v_mfma_f32_16x16x32_bf16 v[58:61], v[148:151], v[176:179], v[58:61]
	s_add_u32 m0, s64, 0x9000
	v_mfma_f32_16x16x32_bf16 v[54:57], v[148:151], v[180:183], v[54:57]
	global_load_lds_dwordx4 v141, s[60:61]
	v_mfma_f32_16x16x32_bf16 v[50:53], v[148:151], v[184:187], v[50:53]
	s_add_u32 m0, s64, 0xa000
	v_mfma_f32_16x16x32_bf16 v[46:49], v[152:155], v[172:175], v[46:49]
	global_load_lds_dwordx4 v142, s[60:61]
	v_mfma_f32_16x16x32_bf16 v[38:41], v[152:155], v[176:179], v[38:41]
	s_add_u32 m0, s64, 0xb000
	v_mfma_f32_16x16x32_bf16 v[34:37], v[152:155], v[180:183], v[34:37]
	global_load_lds_dwordx4 v143, s[60:61]
	v_mfma_f32_16x16x32_bf16 v[30:33], v[152:155], v[184:187], v[30:33]
	s_add_u32 s60, s60, 0x80
	s_addc_u32 s61, s61, 0
	s_waitcnt vmcnt(4)
	s_barrier
	ds_read_b128 v[66:69], v136 offset:0
	ds_read_b128 v[82:85], v137 offset:16384
	ds_read_b128 v[86:89], v137 offset:18432
	ds_read_b128 v[70:73], v136 offset:2048
	ds_read_b128 v[90:93], v137 offset:20480
	ds_read_b128 v[94:97], v137 offset:22528
	ds_read_b128 v[74:77], v136 offset:4096
	ds_read_b128 v[78:81], v136 offset:6144
	v_mfma_f32_16x16x32_bf16 v[26:29], v[156:159], v[172:175], v[26:29]
	v_mfma_f32_16x16x32_bf16 v[22:25], v[156:159], v[176:179], v[22:25]
	v_mfma_f32_16x16x32_bf16 v[18:21], v[156:159], v[180:183], v[18:21]
	v_mfma_f32_16x16x32_bf16 v[14:17], v[156:159], v[184:187], v[14:17]
	v_mfma_f32_16x16x32_bf16 v[10:13], v[168:171], v[172:175], v[10:13]
	v_mfma_f32_16x16x32_bf16 v[6:9], v[168:171], v[176:179], v[6:9]
	v_mfma_f32_16x16x32_bf16 v[2:5], v[168:171], v[180:183], v[2:5]
	v_mfma_f32_16x16x32_bf16 v[42:45], v[168:171], v[184:187], v[42:45]
	s_sub_i32 s65, s65, 1
	s_cmp_lg_u32 s65, 0
	s_cbranch_scc1 .Levwin_loop
	ds_read_b128 v[148:151], v138 offset:0
	ds_read_b128 v[172:175], v139 offset:16384
	ds_read_b128 v[176:179], v139 offset:18432
	ds_read_b128 v[152:155], v138 offset:2048
	ds_read_b128 v[180:183], v139 offset:20480
	ds_read_b128 v[184:187], v139 offset:22528
	ds_read_b128 v[156:159], v138 offset:4096
	ds_read_b128 v[168:171], v138 offset:6144
	s_waitcnt lgkmcnt(8)
	s_add_u32 m0, s64, 0xc000
	v_mfma_f32_16x16x32_bf16 v[62:65], v[66:69], v[82:85], v[62:65]
	v_mfma_f32_16x16x32_bf16 v[58:61], v[66:69], v[86:89], v[58:61]
	global_load_lds_dwordx4 v144, s[62:63]
	v_mfma_f32_16x16x32_bf16 v[54:57], v[66:69], v[90:93], v[54:57]
	v_mfma_f32_16x16x32_bf16 v[50:53], v[66:69], v[94:97], v[50:53]
	s_add_u32 m0, s64, 0xd000
	v_mfma_f32_16x16x32_bf16 v[46:49], v[70:73], v[82:85], v[46:49]
	v_mfma_f32_16x16x32_bf16 v[38:41], v[70:73], v[86:89], v[38:41]
	global_load_lds_dwordx4 v145, s[62:63]
	v_mfma_f32_16x16x32_bf16 v[34:37], v[70:73], v[90:93], v[34:37]
	v_mfma_f32_16x16x32_bf16 v[30:33], v[70:73], v[94:97], v[30:33]
	s_add_u32 m0, s64, 0xe000
	v_mfma_f32_16x16x32_bf16 v[26:29], v[74:77], v[82:85], v[26:29]
	v_mfma_f32_16x16x32_bf16 v[22:25], v[74:77], v[86:89], v[22:25]
	global_load_lds_dwordx4 v146, s[62:63]
	v_mfma_f32_16x16x32_bf16 v[18:21], v[74:77], v[90:93], v[18:21]
	v_mfma_f32_16x16x32_bf16 v[14:17], v[74:77], v[94:97], v[14:17]
	s_add_u32 m0, s64, 0xf000
	v_mfma_f32_16x16x32_bf16 v[10:13], v[78:81], v[82:85], v[10:13]
	v_mfma_f32_16x16x32_bf16 v[6:9], v[78:81], v[86:89], v[6:9]
	global_load_lds_dwordx4 v147, s[62:63]
	v_mfma_f32_16x16x32_bf16 v[2:5], v[78:81], v[90:93], v[2:5]
	v_mfma_f32_16x16x32_bf16 v[42:45], v[78:81], v[94:97], v[42:45]
	s_add_u32 s62, s62, 0x80
	s_addc_u32 s63, s63, 0
	s_waitcnt lgkmcnt(0)
	s_barrier
	v_mfma_f32_16x16x32_bf16 v[62:65], v[148:151], v[172:175], v[62:65]
	v_mfma_f32_16x16x32_bf16 v[58:61], v[148:151], v[176:179], v[58:61]
	v_mfma_f32_16x16x32_bf16 v[54:57], v[148:151], v[180:183], v[54:57]
	v_mfma_f32_16x16x32_bf16 v[50:53], v[148:151], v[184:187], v[50:53]
	v_mfma_f32_16x16x32_bf16 v[46:49], v[152:155], v[172:175], v[46:49]
	v_mfma_f32_16x16x32_bf16 v[38:41], v[152:155], v[176:179], v[38:41]
	v_mfma_f32_16x16x32_bf16 v[34:37], v[152:155], v[180:183], v[34:37]
	v_mfma_f32_16x16x32_bf16 v[30:33], v[152:155], v[184:187], v[30:33]
	s_waitcnt vmcnt(0)
	s_barrier
	ds_read_b128 v[66:69], v136 offset:32768
	ds_read_b128 v[82:85], v137 offset:49152
	ds_read_b128 v[86:89], v137 offset:51200
	ds_read_b128 v[70:73], v136 offset:34816
	ds_read_b128 v[90:93], v137 offset:53248
	ds_read_b128 v[94:97], v137 offset:55296
	ds_read_b128 v[74:77], v136 offset:36864
	ds_read_b128 v[78:81], v136 offset:38912
	v_mfma_f32_16x16x32_bf16 v[26:29], v[156:159], v[172:175], v[26:29]
	v_mfma_f32_16x16x32_bf16 v[22:25], v[156:159], v[176:179], v[22:25]
	v_mfma_f32_16x16x32_bf16 v[18:21], v[156:159], v[180:183], v[18:21]
	v_mfma_f32_16x16x32_bf16 v[14:17], v[156:159], v[184:187], v[14:17]
	v_mfma_f32_16x16x32_bf16 v[10:13], v[168:171], v[172:175], v[10:13]
	v_mfma_f32_16x16x32_bf16 v[6:9], v[168:171], v[176:179], v[6:9]
	v_mfma_f32_16x16x32_bf16 v[2:5], v[168:171], v[180:183], v[2:5]
	v_mfma_f32_16x16x32_bf16 v[42:45], v[168:171], v[184:187], v[42:45]
	ds_read_b128 v[148:151], v138 offset:32768
	ds_read_b128 v[172:175], v139 offset:49152
	ds_read_b128 v[176:179], v139 offset:51200
	ds_read_b128 v[152:155], v138 offset:34816
	ds_read_b128 v[180:183], v139 offset:53248
	ds_read_b128 v[184:187], v139 offset:55296
	ds_read_b128 v[156:159], v138 offset:36864
	ds_read_b128 v[168:171], v138 offset:38912
	s_waitcnt lgkmcnt(8)
	v_mfma_f32_16x16x32_bf16 v[62:65], v[66:69], v[82:85], v[62:65]
	v_mfma_f32_16x16x32_bf16 v[58:61], v[66:69], v[86:89], v[58:61]
	v_mfma_f32_16x16x32_bf16 v[54:57], v[66:69], v[90:93], v[54:57]
	v_mfma_f32_16x16x32_bf16 v[50:53], v[66:69], v[94:97], v[50:53]
	v_mfma_f32_16x16x32_bf16 v[46:49], v[70:73], v[82:85], v[46:49]
	v_mfma_f32_16x16x32_bf16 v[38:41], v[70:73], v[86:89], v[38:41]
	v_mfma_f32_16x16x32_bf16 v[34:37], v[70:73], v[90:93], v[34:37]
	v_mfma_f32_16x16x32_bf16 v[30:33], v[70:73], v[94:97], v[30:33]
	v_mfma_f32_16x16x32_bf16 v[26:29], v[74:77], v[82:85], v[26:29]
	v_mfma_f32_16x16x32_bf16 v[22:25], v[74:77], v[86:89], v[22:25]
	v_mfma_f32_16x16x32_bf16 v[18:21], v[74:77], v[90:93], v[18:21]
	v_mfma_f32_16x16x32_bf16 v[14:17], v[74:77], v[94:97], v[14:17]
	v_mfma_f32_16x16x32_bf16 v[10:13], v[78:81], v[82:85], v[10:13]
	v_mfma_f32_16x16x32_bf16 v[6:9], v[78:81], v[86:89], v[6:9]
	v_mfma_f32_16x16x32_bf16 v[2:5], v[78:81], v[90:93], v[2:5]
	v_mfma_f32_16x16x32_bf16 v[42:45], v[78:81], v[94:97], v[42:45]
	s_waitcnt lgkmcnt(0)
	s_barrier
	v_mfma_f32_16x16x32_bf16 v[62:65], v[148:151], v[172:175], v[62:65]
	v_mfma_f32_16x16x32_bf16 v[58:61], v[148:151], v[176:179], v[58:61]
	v_mfma_f32_16x16x32_bf16 v[54:57], v[148:151], v[180:183], v[54:57]
	v_mfma_f32_16x16x32_bf16 v[50:53], v[148:151], v[184:187], v[50:53]
	v_mfma_f32_16x16x32_bf16 v[46:49], v[152:155], v[172:175], v[46:49]
	v_mfma_f32_16x16x32_bf16 v[38:41], v[152:155], v[176:179], v[38:41]
	v_mfma_f32_16x16x32_bf16 v[34:37], v[152:155], v[180:183], v[34:37]
	v_mfma_f32_16x16x32_bf16 v[30:33], v[152:155], v[184:187], v[30:33]
	v_mfma_f32_16x16x32_bf16 v[26:29], v[156:159], v[172:175], v[26:29]
	v_mfma_f32_16x16x32_bf16 v[22:25], v[156:159], v[176:179], v[22:25]
	v_mfma_f32_16x16x32_bf16 v[18:21], v[156:159], v[180:183], v[18:21]
	v_mfma_f32_16x16x32_bf16 v[14:17], v[156:159], v[184:187], v[14:17]
	v_mfma_f32_16x16x32_bf16 v[10:13], v[168:171], v[172:175], v[10:13]
	v_mfma_f32_16x16x32_bf16 v[6:9], v[168:171], v[176:179], v[6:9]
	v_mfma_f32_16x16x32_bf16 v[2:5], v[168:171], v[180:183], v[2:5]
	v_mfma_f32_16x16x32_bf16 v[42:45], v[168:171], v[184:187], v[42:45]

.LBB0_882:
	s_mov_b64 s[14:15], 0x80
	v_lshl_add_u64 v[114:115], v[70:71], 0, s[14:15]
	v_mov_b32_e32 v38, 0
	s_mov_b32 s7, s6
	v_lshl_add_u64 v[116:117], v[114:115], 0, v[98:99]
	v_lshl_add_u64 v[118:119], v[114:115], 0, v[100:101]
	v_lshl_add_u64 v[120:121], v[114:115], 0, v[102:103]
	s_mov_b64 s[4:5], 0
	s_mov_b32 s6, 0
	v_readfirstlane_b32 s60, v104
	v_readfirstlane_b32 s61, v105
	v_readfirstlane_b32 s62, v114
	v_readfirstlane_b32 s63, v115
	v_readfirstlane_b32 s64, v122
	v_subrev_u32_e32 v140, s60, v104
	v_subrev_u32_e32 v144, s62, v114
	v_subrev_u32_e32 v145, s62, v116
	v_subrev_u32_e32 v146, s62, v118
	v_subrev_u32_e32 v147, s62, v120
	v_add_u32_e32 v141, 0x10000, v140
	v_add_u32_e32 v142, 0x20000, v140
	v_add_u32_e32 v143, 0x30000, v140
	v_add3_u32 v136, v131, v132, v133
	v_add3_u32 v137, v131, v134, v133
	v_add3_u32 v138, v130, v132, v133
	v_add3_u32 v139, v130, v134, v133
	s_add_u32 s60, s60, 0x80
	s_addc_u32 s61, s61, 0
	s_add_u32 m0, s64, 0x8000
	v_mov_b32_e32 v39, v38
	global_load_lds_dwordx4 v140, s[60:61]
	v_mov_b32_e32 v40, v38
	v_mov_b32_e32 v41, v38
	v_mov_b32_e32 v2, v38
	s_add_u32 m0, s64, 0x9000
	v_mov_b32_e32 v3, v38
	global_load_lds_dwordx4 v141, s[60:61]
	v_mov_b32_e32 v4, v38
	v_mov_b32_e32 v5, v38
	v_mov_b32_e32 v6, v38
	s_add_u32 m0, s64, 0xa000
	v_mov_b32_e32 v7, v38
	global_load_lds_dwordx4 v142, s[60:61]
	v_mov_b32_e32 v8, v38
	v_mov_b32_e32 v9, v38
	v_mov_b32_e32 v10, v38
	s_add_u32 m0, s64, 0xb000
	v_mov_b32_e32 v11, v38
	global_load_lds_dwordx4 v143, s[60:61]
	v_mov_b32_e32 v12, v38
	v_mov_b32_e32 v13, v38
	v_mov_b32_e32 v14, v38
	v_mov_b32_e32 v15, v38
	v_mov_b32_e32 v16, v38
	v_mov_b32_e32 v17, v38
	v_mov_b32_e32 v18, v38
	v_mov_b32_e32 v19, v38
	v_mov_b32_e32 v20, v38
	v_mov_b32_e32 v21, v38
	v_mov_b32_e32 v22, v38
	v_mov_b32_e32 v23, v38
	v_mov_b32_e32 v24, v38
	v_mov_b32_e32 v25, v38
	v_mov_b32_e32 v26, v38
	v_mov_b32_e32 v27, v38
	v_mov_b32_e32 v28, v38
	v_mov_b32_e32 v29, v38
	v_mov_b32_e32 v30, v38
	v_mov_b32_e32 v31, v38
	v_mov_b32_e32 v32, v38
	v_mov_b32_e32 v33, v38
	v_mov_b32_e32 v34, v38
	v_mov_b32_e32 v35, v38
	v_mov_b32_e32 v36, v38
	v_mov_b32_e32 v37, v38
	v_mov_b32_e32 v42, v38
	v_mov_b32_e32 v43, v38
	v_mov_b32_e32 v44, v38
	v_mov_b32_e32 v45, v38
	v_mov_b32_e32 v46, v38
	v_mov_b32_e32 v47, v38
	v_mov_b32_e32 v48, v38
	v_mov_b32_e32 v49, v38
	v_mov_b32_e32 v50, v38
	v_mov_b32_e32 v51, v38
	v_mov_b32_e32 v52, v38
	v_mov_b32_e32 v53, v38
	v_mov_b32_e32 v54, v38
	v_mov_b32_e32 v55, v38
	v_mov_b32_e32 v56, v38
	v_mov_b32_e32 v57, v38
	v_mov_b32_e32 v58, v38
	v_mov_b32_e32 v59, v38
	v_mov_b32_e32 v60, v38
	v_mov_b32_e32 v61, v38
	v_mov_b32_e32 v62, v38
	v_mov_b32_e32 v63, v38
	v_mov_b32_e32 v64, v38
	v_mov_b32_e32 v65, v38
	s_add_u32 s60, s60, 0x80
	s_addc_u32 s61, s61, 0
	s_mov_b64 s[22:23], 0x10000
	s_mov_b64 s[24:25], 0x20000
	s_mov_b64 s[26:27], 0x30000
	s_mov_b64 s[16:17], 0x10080
	s_mov_b64 s[18:19], 0x20080
	s_mov_b64 s[20:21], 0x30080
	s_waitcnt vmcnt(4) lgkmcnt(0)
	s_barrier
	ds_read_b128 v[66:69], v136 offset:0
	ds_read_b128 v[82:85], v137 offset:16384
	ds_read_b128 v[86:89], v137 offset:18432
	ds_read_b128 v[70:73], v136 offset:2048
	ds_read_b128 v[90:93], v137 offset:20480
	ds_read_b128 v[94:97], v137 offset:22528
	ds_read_b128 v[74:77], v136 offset:4096
	ds_read_b128 v[78:81], v136 offset:6144
	s_mov_b32 s65, 7
